# flat2global: the 60 flat loads of the P3/P4 epilogues issued as global loads (stores unchanged)
# speedup vs baseline: 1.0002x; 1.0002x over previous
; __device__ __forceinline__ unsigned cvtpk(float lo, float hi) { f32x2 v = {lo, hi}; bf16x2_t b = __builtin_convertvector(v, bf16x2_t); return __builtin_bit_cast(unsigned, b); }
;     __device__ __forceinline__ void operator()(const Acc& acc, const Unit& u, int wr, int wc, int fr, int fq) const {
;     ...
;             for (int m = 0; m < 4; ++m) { const size_t off = (size_t)(u.pm * 256 + ai * 128 + wr * 64 + m * 16 + fr) * DM + colbase;
; #pragma unroll
;                 for (int bj = 0; bj < 2; ++bj) { xv[m][bj][0] = __builtin_nontemporal_load((const f32x4*)(x + off + 32 * bj)); xv[m][bj][1] = __builtin_nontemporal_load((const f32x4*)(x + off + 32 * bj + 4)); } }
; #pragma unroll
;             for (int m = 0; m < 4; ++m) {
;                 const int row = u.pm * 256 + ai * 128 + wr * 64 + m * 16 + fr;
;                 float ss = 0.f;
; #pragma unroll
;                 for (int bj = 0; bj < 2; ++bj) {
;                     const size_t off = (size_t)row * DM + colbase + 32 * bj;
;                     const f32x4 h0 = xv[m][bj][0] + acc[ai][bj][m][0], h1 = xv[m][bj][1] + acc[ai][bj][m][1];
;                     u32x4 w; w.x = cvtpk(h0.x, h0.y); w.y = cvtpk(h0.z, h0.w); w.z = cvtpk(h1.x, h1.y); w.w = cvtpk(h1.z, h1.w);
;                     *(u32x4*)(HB + off) = w;
;                     ss += (h0.x * h0.x + h0.y * h0.y) + (h0.z * h0.z + h0.w * h0.w) + (h1.x * h1.x + h1.y * h1.y) + (h1.z * h1.z + h1.w * h1.w);
;                 }
;                 ss = quad_sum(ss);
;                 if (fq == 0) atomicAdd(rowss + row, ss);
.LBB0_725:
	v_mov_b32_e32 v128, v200
	s_lshl_b32 s13, s22, 8
	s_or_b32 s13, s13, s86
	v_and_b32_e32 v129, 15, v128
	v_bfe_u32 v202, v128, 4, 2
	s_nop 0
	v_lshl_add_u32 v188, v202, 3, s13
	s_lshl_b32 s13, s20, 8
	s_add_i32 s13, s13, s79
	v_add_u32_e32 v192, s13, v129
	v_ashrrev_i32_e32 v189, 31, v188
	v_ashrrev_i32_e32 v193, 31, v192
	v_lshl_add_u64 v[190:191], v[188:189], 2, s[8:9]
	v_lshlrev_b64 v[128:129], 13, v[192:193]
	v_lshl_add_u64 v[128:129], v[190:191], 0, v[128:129]
	global_load_dwordx4 v[206:209], v[128:129], off nt
	global_load_dwordx4 v[210:213], v[128:129], off offset:16 nt
	global_load_dwordx4 v[214:217], v[128:129], off offset:128 nt
	global_load_dwordx4 v[218:221], v[128:129], off offset:144 nt
	v_add_u32_e32 v198, 16, v192
	v_add_u32_e32 v196, 32, v192
	v_add_u32_e32 v194, 48, v192
	v_ashrrev_i32_e32 v199, 31, v198
	v_ashrrev_i32_e32 v197, 31, v196
	v_ashrrev_i32_e32 v195, 31, v194
	v_lshlrev_b64 v[128:129], 13, v[198:199]
	v_lshlrev_b64 v[130:131], 13, v[196:197]
	v_lshlrev_b64 v[132:133], 13, v[194:195]
	v_lshl_add_u64 v[128:129], v[190:191], 0, v[128:129]
	v_lshl_add_u64 v[130:131], v[190:191], 0, v[130:131]
	v_lshl_add_u64 v[222:223], v[190:191], 0, v[132:133]
	global_load_dwordx4 v[172:175], v[128:129], off nt
	global_load_dwordx4 v[168:171], v[128:129], off offset:16 nt
	global_load_dwordx4 v[164:167], v[128:129], off offset:128 nt
	global_load_dwordx4 v[160:163], v[128:129], off offset:144 nt
	global_load_dwordx4 v[156:159], v[130:131], off nt
	global_load_dwordx4 v[152:155], v[130:131], off offset:16 nt
	global_load_dwordx4 v[148:151], v[130:131], off offset:128 nt
	global_load_dwordx4 v[144:147], v[130:131], off offset:144 nt
	global_load_dwordx4 v[140:143], v[222:223], off nt
	global_load_dwordx4 v[136:139], v[222:223], off offset:16 nt
	global_load_dwordx4 v[132:135], v[222:223], off offset:128 nt
	s_nop 0
	global_load_dwordx4 v[128:131], v[222:223], off offset:144 nt
	v_cmp_eq_u32_e32 vcc, 0, v202
	v_lshlrev_b64 v[222:223], 12, v[192:193]
	v_lshl_add_u64 v[222:223], s[10:11], 0, v[222:223]
	v_lshl_add_u64 v[222:223], v[188:189], 1, v[222:223]
	s_waitcnt vmcnt(0) lgkmcnt(0)
	v_pk_add_f32 v[126:127], v[126:127], v[208:209]
	v_pk_add_f32 v[124:125], v[124:125], v[206:207]
	v_pk_add_f32 v[118:119], v[118:119], v[216:217]
	v_pk_add_f32 v[206:207], v[116:117], v[214:215]
	v_pk_add_f32 v[120:121], v[120:121], v[210:211]
	v_pk_add_f32 v[210:211], v[112:113], v[218:219]
	v_cvt_pk_bf16_f32 v112, v124, v125
	v_cvt_pk_bf16_f32 v113, v126, v127
	v_mul_f32_e32 v125, v125, v125
	v_mul_f32_e32 v127, v127, v127
	v_cvt_pk_bf16_f32 v117, v118, v119
	v_mul_f32_e32 v202, v207, v207
	v_mul_f32_e32 v119, v119, v119
	v_pk_add_f32 v[122:123], v[122:123], v[212:213]
	v_pk_add_f32 v[208:209], v[114:115], v[220:221]
	v_cvt_pk_bf16_f32 v114, v120, v121
	v_mul_f32_e32 v121, v121, v121
	v_cvt_pk_bf16_f32 v116, v206, v207
	v_mul_f32_e32 v207, v211, v211
	v_fmac_f32_e32 v125, v124, v124
	v_fmac_f32_e32 v127, v126, v126
	v_fmac_f32_e32 v202, v206, v206
	v_fmac_f32_e32 v119, v118, v118
	v_cvt_pk_bf16_f32 v115, v122, v123
	v_mul_f32_e32 v123, v123, v123
	v_mul_f32_e32 v212, v209, v209
	v_fmac_f32_e32 v121, v120, v120
	v_fmac_f32_e32 v207, v210, v210
	v_add_f32_e32 v118, v125, v127
	v_add_f32_e32 v119, v202, v119
	v_fmac_f32_e32 v123, v122, v122
	v_fmac_f32_e32 v212, v208, v208
	v_add_f32_e32 v118, v118, v121
	v_add_f32_e32 v119, v119, v207
	v_add_f32_e32 v118, v123, v118
	v_add_f32_e32 v119, v212, v119
	v_add_f32_e32 v120, v118, v119
	ds_swizzle_b32 v121, v120 offset:swizzle(SWAP,16)
	v_cvt_pk_bf16_f32 v118, v210, v211
	v_cvt_pk_bf16_f32 v119, v208, v209
	v_mov_b64_e32 v[224:225], v[112:113]
	v_mov_b64_e32 v[226:227], v[114:115]
	flat_store_dwordx4 v[222:223], v[112:115]
	v_mov_b64_e32 v[214:215], v[116:117]
	v_mov_b64_e32 v[216:217], v[118:119]
	flat_store_dwordx4 v[222:223], v[116:119] offset:64
	s_waitcnt lgkmcnt(0)
	v_add_f32_e32 v114, v120, v121
	v_mov_b32_e32 v115, v114
	s_nop 1
	v_permlane32_swap_b32_e32 v114, v115
	v_lshl_add_u64 v[112:113], v[192:193], 2, s[6:7]
	s_and_saveexec_b64 s[20:21], vcc
	s_cbranch_execz .LBB0_727
	v_add_f32_e32 v114, v114, v115
	flat_atomic_add_f32 v[112:113], v114

; __device__ __forceinline__ unsigned cvtpk(float lo, float hi) { f32x2 v = {lo, hi}; bf16x2_t b = __builtin_convertvector(v, bf16x2_t); return __builtin_bit_cast(unsigned, b); }
;     __device__ __forceinline__ void operator()(const Acc& acc, const Unit& u, int wr, int wc, int fr, int fq) const {
;     ...
;             for (int m = 0; m < 4; ++m) { const size_t off = (size_t)(u.pm * 256 + ai * 128 + wr * 64 + m * 16 + fr) * DM + colbase;
; #pragma unroll
;                 for (int bj = 0; bj < 2; ++bj) { xv[m][bj][0] = __builtin_nontemporal_load((const f32x4*)(x + off + 32 * bj)); xv[m][bj][1] = __builtin_nontemporal_load((const f32x4*)(x + off + 32 * bj + 4)); } }
; #pragma unroll
;             for (int m = 0; m < 4; ++m) {
;                 const int row = u.pm * 256 + ai * 128 + wr * 64 + m * 16 + fr;
;                 float ss = 0.f;
; #pragma unroll
;                 for (int bj = 0; bj < 2; ++bj) {
;                     const size_t off = (size_t)row * DM + colbase + 32 * bj;
;                     const f32x4 h0 = xv[m][bj][0] + acc[ai][bj][m][0], h1 = xv[m][bj][1] + acc[ai][bj][m][1];
;                     u32x4 w; w.x = cvtpk(h0.x, h0.y); w.y = cvtpk(h0.z, h0.w); w.z = cvtpk(h1.x, h1.y); w.w = cvtpk(h1.z, h1.w);
;                     *(u32x4*)(HB + off) = w;
;                     ss += (h0.x * h0.x + h0.y * h0.y) + (h0.z * h0.z + h0.w * h0.w) + (h1.x * h1.x + h1.y * h1.y) + (h1.z * h1.z + h1.w * h1.w);
;                 }
;                 ss = quad_sum(ss);
;                 if (fq == 0) atomicAdd(rowss + row, ss);
.LBB0_733:
	s_or_b64 exec, exec, s[20:21]
	v_add_u32_e32 v136, 0x80, v192
	v_ashrrev_i32_e32 v137, 31, v136
	v_lshlrev_b64 v[64:65], 13, v[136:137]
	v_lshl_add_u64 v[64:65], v[190:191], 0, v[64:65]
	global_load_dwordx4 v[120:123], v[64:65], off nt
	global_load_dwordx4 v[124:127], v[64:65], off offset:16 nt
	global_load_dwordx4 v[128:131], v[64:65], off offset:128 nt
	global_load_dwordx4 v[132:135], v[64:65], off offset:144 nt
	v_add_u32_e32 v118, 0x90, v192
	v_add_u32_e32 v116, 0xa0, v192
	v_add_u32_e32 v114, 0xb0, v192
	v_ashrrev_i32_e32 v119, 31, v118
	v_ashrrev_i32_e32 v117, 31, v116
	v_ashrrev_i32_e32 v115, 31, v114
	v_lshlrev_b64 v[64:65], 13, v[118:119]
	v_lshlrev_b64 v[66:67], 13, v[116:117]
	v_lshlrev_b64 v[68:69], 13, v[114:115]
	v_lshl_add_u64 v[64:65], v[190:191], 0, v[64:65]
	v_lshl_add_u64 v[66:67], v[190:191], 0, v[66:67]
	v_lshl_add_u64 v[138:139], v[190:191], 0, v[68:69]
	global_load_dwordx4 v[108:111], v[64:65], off nt
	global_load_dwordx4 v[104:107], v[64:65], off offset:16 nt
	global_load_dwordx4 v[100:103], v[64:65], off offset:128 nt
	global_load_dwordx4 v[96:99], v[64:65], off offset:144 nt
	global_load_dwordx4 v[92:95], v[66:67], off nt
	global_load_dwordx4 v[88:91], v[66:67], off offset:16 nt
	global_load_dwordx4 v[84:87], v[66:67], off offset:128 nt
	global_load_dwordx4 v[80:83], v[66:67], off offset:144 nt
	global_load_dwordx4 v[76:79], v[138:139], off nt
	global_load_dwordx4 v[72:75], v[138:139], off offset:16 nt
	global_load_dwordx4 v[68:71], v[138:139], off offset:128 nt
	s_nop 0
	global_load_dwordx4 v[64:67], v[138:139], off offset:144 nt
	v_lshlrev_b64 v[136:137], 12, v[136:137]
	v_lshl_add_u64 v[136:137], s[10:11], 0, v[136:137]
	v_lshl_add_u64 v[136:137], v[188:189], 1, v[136:137]
	s_waitcnt vmcnt(0) lgkmcnt(0)
	v_pk_add_f32 v[62:63], v[62:63], v[122:123]
	v_pk_add_f32 v[60:61], v[60:61], v[120:121]
	v_pk_add_f32 v[54:55], v[54:55], v[130:131]
	v_pk_add_f32 v[120:121], v[52:53], v[128:129]
	v_pk_add_f32 v[56:57], v[56:57], v[124:125]
	v_pk_add_f32 v[124:125], v[48:49], v[132:133]
	v_cvt_pk_bf16_f32 v48, v60, v61
	v_cvt_pk_bf16_f32 v49, v62, v63
	v_mul_f32_e32 v61, v61, v61
	v_mul_f32_e32 v63, v63, v63
	v_cvt_pk_bf16_f32 v52, v120, v121
	v_cvt_pk_bf16_f32 v53, v54, v55
	v_mul_f32_e32 v121, v121, v121
	v_mul_f32_e32 v55, v55, v55
	v_pk_add_f32 v[58:59], v[58:59], v[126:127]
	v_pk_add_f32 v[122:123], v[50:51], v[134:135]
	v_cvt_pk_bf16_f32 v50, v56, v57
	v_mul_f32_e32 v57, v57, v57
	v_mul_f32_e32 v126, v125, v125
	v_fmac_f32_e32 v61, v60, v60
	v_fmac_f32_e32 v63, v62, v62
	v_fmac_f32_e32 v121, v120, v120
	v_fmac_f32_e32 v55, v54, v54
	v_cvt_pk_bf16_f32 v51, v58, v59
	v_mul_f32_e32 v59, v59, v59
	v_mul_f32_e32 v127, v123, v123
	v_fmac_f32_e32 v57, v56, v56
	v_fmac_f32_e32 v126, v124, v124
	v_add_f32_e32 v54, v61, v63
	v_add_f32_e32 v55, v121, v55
	v_fmac_f32_e32 v59, v58, v58
	v_fmac_f32_e32 v127, v122, v122
	v_add_f32_e32 v54, v54, v57
	v_add_f32_e32 v55, v55, v126
	v_add_f32_e32 v54, v59, v54
	v_add_f32_e32 v55, v127, v55
	v_add_f32_e32 v56, v54, v55
	ds_swizzle_b32 v57, v56 offset:swizzle(SWAP,16)
	v_cvt_pk_bf16_f32 v54, v124, v125
	v_cvt_pk_bf16_f32 v55, v122, v123
	v_mov_b64_e32 v[248:249], v[48:49]
	v_mov_b64_e32 v[252:253], v[50:51]
	flat_store_dwordx4 v[136:137], v[48:51]
	v_mov_b64_e32 v[218:219], v[52:53]
	v_mov_b64_e32 v[220:221], v[54:55]
	flat_store_dwordx4 v[136:137], v[52:55] offset:64
	s_waitcnt lgkmcnt(0)
	v_add_f32_e32 v48, v56, v57
	v_mov_b32_e32 v49, v48
	s_nop 1
	v_permlane32_swap_b32_e32 v48, v49
	s_and_saveexec_b64 s[20:21], vcc
	s_cbranch_execz .LBB0_735
	v_add_f32_e32 v48, v48, v49
	flat_atomic_add_f32 v[112:113], v48 offset:512

; __device__ __forceinline__ float bflo(unsigned u) { return __uint_as_float(u << 16); }
;     __device__ __forceinline__ void operator()(const Acc& acc, const Unit& u, int wr, int wc, int fr, int fq) const {
;     ...
;             for (int m = 0; m < 4; ++m) { const int row = u.pm * 256 + ai * 128 + wr * 64 + m * 16 + fr; const size_t off = (size_t)row * DM + colbase;
;                 rsv[m] = rowss[row];
; #pragma unroll
;                 for (int bj = 0; bj < 2; ++bj) { const u32x4 hw = __builtin_nontemporal_load((const u32x4*)(hin + off + 32 * bj));
;                     hv[m][bj][0] = (f32x4){bflo(hw.x), bfhi(hw.x), bflo(hw.y), bfhi(hw.y)}; hv[m][bj][1] = (f32x4){bflo(hw.z), bfhi(hw.z), bflo(hw.w), bfhi(hw.w)};
;                     pw[m][bj] = __builtin_nontemporal_load((const u32x4*)(PP + off + 32 * bj)); } }
; #pragma unroll
;             for (int m = 0; m < 4; ++m) {
;                 const int row = u.pm * 256 + ai * 128 + wr * 64 + m * 16 + fr;
;                 const float rs = rsqrtf(rsv[m] * (1.0f / DM) + EPS) * -1.4426950408889634f;
; #pragma unroll
;                 for (int bj = 0; bj < 2; ++bj) {
;                     const size_t off = (size_t)row * DM + colbase + 32 * bj;
;                     f32x4 h0 = hv[m][bj][0], h1 = hv[m][bj][1];
;                     const u32x4 p4 = pw[m][bj];
;                     const f32x4 a0 = acc[ai][bj][m][0], a1 = acc[ai][bj][m][1];
;                     h0.x += bflo(p4.x) * __builtin_amdgcn_rcpf(1.0f + __builtin_amdgcn_exp2f(a0.x * rs));
;                     h0.y += bfhi(p4.x) * __builtin_amdgcn_rcpf(1.0f + __builtin_amdgcn_exp2f(a0.y * rs));
;                     h0.z += bflo(p4.y) * __builtin_amdgcn_rcpf(1.0f + __builtin_amdgcn_exp2f(a0.z * rs));
;                     h0.w += bfhi(p4.y) * __builtin_amdgcn_rcpf(1.0f + __builtin_amdgcn_exp2f(a0.w * rs));
;                     h1.x += bflo(p4.z) * __builtin_amdgcn_rcpf(1.0f + __builtin_amdgcn_exp2f(a1.x * rs));
;                     h1.y += bfhi(p4.z) * __builtin_amdgcn_rcpf(1.0f + __builtin_amdgcn_exp2f(a1.y * rs));
;                     h1.z += bflo(p4.w) * __builtin_amdgcn_rcpf(1.0f + __builtin_amdgcn_exp2f(a1.z * rs));
;                     h1.w += bfhi(p4.w) * __builtin_amdgcn_rcpf(1.0f + __builtin_amdgcn_exp2f(a1.w * rs));
;                     *(f32x4*)(out + off) = h0; *(f32x4*)(out + off + 4) = h1;
.LBB0_814:
	v_mov_b64_e32 v[206:207], v[224:225]
	v_mov_b64_e32 v[208:209], v[226:227]
	v_mov_b64_e32 v[172:173], v[228:229]
	v_mov_b64_e32 v[174:175], v[230:231]
	v_mov_b64_e32 v[164:165], v[232:233]
	v_mov_b64_e32 v[166:167], v[234:235]
	v_mov_b64_e32 v[156:157], v[236:237]
	v_mov_b64_e32 v[158:159], v[238:239]
	v_mov_b64_e32 v[148:149], v[240:241]
	v_mov_b64_e32 v[150:151], v[242:243]
	v_mov_b64_e32 v[140:141], v[210:211]
	v_mov_b64_e32 v[142:143], v[212:213]
	v_mov_b64_e32 v[236:237], v[218:219]
	v_mov_b64_e32 v[238:239], v[220:221]
	v_mov_b64_e32 v[240:241], v[222:223]
	v_mov_b32_e32 v128, v200
	s_lshl_b32 s11, s42, 8
	v_and_b32_e32 v129, 15, v128
	v_bfe_u32 v128, v128, 4, 2
	s_or_b32 s11, s11, s86
	s_nop 0
	v_lshl_add_u32 v188, v128, 3, s11
	s_lshl_b32 s11, s41, 8
	s_add_i32 s11, s11, s79
	v_add_u32_e32 v190, s11, v129
	v_ashrrev_i32_e32 v191, 31, v190
	v_lshl_add_u64 v[192:193], v[190:191], 2, s[80:81]
	global_load_dword v226, v[192:193], off
	v_ashrrev_i32_e32 v189, 31, v188
	v_lshlrev_b64 v[128:129], 11, v[190:191]
	v_lshl_add_u64 v[222:223], v[128:129], 0, v[188:189]
	v_lshlrev_b64 v[128:129], 1, v[222:223]
	v_lshl_add_u64 v[130:131], s[6:7], 0, v[128:129]
	v_lshl_add_u64 v[128:129], s[8:9], 0, v[128:129]
	global_load_dwordx4 v[210:213], v[128:129], off nt
	global_load_dword v234, v[192:193], off offset:64
	global_load_dword v235, v[192:193], off offset:128
	global_load_dword v191, v[192:193], off offset:192
	global_load_dwordx4 v[218:221], v[128:129], off offset:64 nt
	v_add_u32_e32 v132, 16, v190
	v_add_u32_e32 v134, 32, v190
	v_add_u32_e32 v136, 48, v190
	v_ashrrev_i32_e32 v133, 31, v132
	v_ashrrev_i32_e32 v135, 31, v134
	v_ashrrev_i32_e32 v137, 31, v136
	v_lshlrev_b64 v[132:133], 11, v[132:133]
	v_lshlrev_b64 v[134:135], 11, v[134:135]
	v_lshlrev_b64 v[136:137], 11, v[136:137]
	v_lshl_add_u64 v[198:199], v[132:133], 0, v[188:189]
	v_lshl_add_u64 v[196:197], v[134:135], 0, v[188:189]
	v_lshl_add_u64 v[194:195], v[136:137], 0, v[188:189]
	v_lshlrev_b64 v[132:133], 1, v[198:199]
	v_lshlrev_b64 v[134:135], 1, v[196:197]
	v_lshlrev_b64 v[136:137], 1, v[194:195]
	v_lshl_add_u64 v[128:129], s[6:7], 0, v[132:133]
	v_lshl_add_u64 v[130:131], s[8:9], 0, v[132:133]
	v_lshl_add_u64 v[132:133], s[6:7], 0, v[134:135]
	v_lshl_add_u64 v[134:135], s[8:9], 0, v[134:135]
	v_lshl_add_u64 v[138:139], s[6:7], 0, v[136:137]
	v_lshl_add_u64 v[224:225], s[8:9], 0, v[136:137]
	global_load_dwordx4 v[168:171], v[130:131], off nt
	global_load_dwordx4 v[160:163], v[130:131], off offset:64 nt
	global_load_dwordx4 v[152:155], v[134:135], off nt
	global_load_dwordx4 v[144:147], v[134:135], off offset:64 nt
	s_nop 0
	v_mov_b64_e32 v[132:133], v[244:245]
	v_mov_b64_e32 v[134:135], v[246:247]
	s_nop 0
	global_load_dwordx4 v[136:139], v[224:225], off nt
	global_load_dwordx4 v[128:131], v[224:225], off offset:64 nt
	s_waitcnt vmcnt(0) lgkmcnt(0)
	v_fmamk_f32 v224, v226, 0x3a000000, v205
	v_mul_f32_e32 v225, 0x4b800000, v224
	v_cmp_gt_f32_e32 vcc, s40, v224
	v_lshlrev_b32_e32 v228, 16, v208
	s_nop 0
	v_cndmask_b32_e32 v224, v224, v225, vcc
	v_rsq_f32_e32 v232, v224
	v_and_b32_e32 v229, 0xffff0000, v208
	v_lshlrev_b32_e32 v230, 16, v212
	v_and_b32_e32 v231, 0xffff0000, v212
	v_mul_f32_e32 v208, 0x45800000, v232
	v_cndmask_b32_e32 v208, v232, v208, vcc
	v_mul_f32_e32 v212, 0xbfb8aa3b, v208
	v_mul_f32_e32 v124, v124, v212
	v_mul_f32_e32 v125, v125, v212
	v_mul_f32_e32 v120, v120, v212
	v_mul_f32_e32 v121, v121, v212
	v_exp_f32_e32 v124, v124
	v_exp_f32_e32 v125, v125
	v_exp_f32_e32 v120, v120
	v_exp_f32_e32 v121, v121
	v_add_f32_e32 v124, 1.0, v124
	v_add_f32_e32 v125, 1.0, v125
	v_add_f32_e32 v208, 1.0, v120
	v_add_f32_e32 v233, 1.0, v121
	v_rcp_f32_e32 v120, v124
	v_rcp_f32_e32 v121, v125
	v_lshlrev_b32_e32 v224, 16, v206
	v_and_b32_e32 v225, 0xffff0000, v206
	v_lshlrev_b32_e32 v226, 16, v210
	v_and_b32_e32 v227, 0xffff0000, v210
	v_mul_f32_e32 v126, v126, v212
	v_mul_f32_e32 v127, v127, v212
	v_mul_f32_e32 v122, v122, v212
	v_exp_f32_e32 v126, v126
	v_exp_f32_e32 v127, v127
	v_pk_fma_f32 v[124:125], v[120:121], v[226:227], v[224:225]
	v_mul_f32_e32 v120, v123, v212
	v_exp_f32_e32 v122, v122
	v_exp_f32_e32 v123, v120
	v_mul_f32_e32 v116, v116, v212
	v_mul_f32_e32 v117, v117, v212
	v_exp_f32_e32 v116, v116
	v_exp_f32_e32 v117, v117
	v_mul_f32_e32 v118, v118, v212
	v_mul_f32_e32 v119, v119, v212
	v_add_f32_e32 v126, 1.0, v126
	v_add_f32_e32 v127, 1.0, v127
	v_exp_f32_e32 v118, v118
	v_exp_f32_e32 v119, v119
	v_mul_f32_e32 v112, v112, v212
	v_mul_f32_e32 v113, v113, v212
	v_rcp_f32_e32 v126, v126
	v_rcp_f32_e32 v127, v127
	v_add_f32_e32 v122, 1.0, v122
	v_add_f32_e32 v123, 1.0, v123
	v_exp_f32_e32 v112, v112
	v_exp_f32_e32 v113, v113
	v_rcp_f32_e32 v232, v208
	v_rcp_f32_e32 v233, v233
	v_rcp_f32_e32 v122, v122
	v_rcp_f32_e32 v123, v123
	v_add_f32_e32 v116, 1.0, v116
	v_add_f32_e32 v117, 1.0, v117
	v_lshlrev_b32_e32 v206, 16, v207
	v_and_b32_e32 v207, 0xffff0000, v207
	v_lshlrev_b32_e32 v210, 16, v211
	v_and_b32_e32 v211, 0xffff0000, v211
	v_rcp_f32_e32 v116, v116
	v_rcp_f32_e32 v117, v117
	v_add_f32_e32 v118, 1.0, v118
	v_add_f32_e32 v119, 1.0, v119
	v_pk_fma_f32 v[126:127], v[126:127], v[210:211], v[206:207]
	v_lshlrev_b32_e32 v206, 16, v209
	v_and_b32_e32 v207, 0xffff0000, v209
	v_lshlrev_b32_e32 v208, 16, v213
	v_and_b32_e32 v209, 0xffff0000, v213
	v_rcp_f32_e32 v118, v118
	v_rcp_f32_e32 v119, v119
	v_add_f32_e32 v112, 1.0, v112
	v_add_f32_e32 v113, 1.0, v113
	v_pk_fma_f32 v[120:121], v[232:233], v[230:231], v[228:229]
	v_pk_fma_f32 v[122:123], v[122:123], v[208:209], v[206:207]
	v_lshl_add_u64 v[206:207], v[222:223], 2, s[2:3]
	v_rcp_f32_e32 v112, v112
; __device__ __forceinline__ float bflo(unsigned u) { return __uint_as_float(u << 16); }
; __device__ __forceinline__ float bfhi(unsigned u) { return __uint_as_float(u & 0xffff0000u); }
;     __device__ __forceinline__ void operator()(const Acc& acc, const Unit& u, int wr, int wc, int fr, int fq) const {
;     ...
;             for (int m = 0; m < 4; ++m) {
;                 const int row = u.pm * 256 + ai * 128 + wr * 64 + m * 16 + fr;
;                 const float rs = rsqrtf(rsv[m] * (1.0f / DM) + EPS) * -1.4426950408889634f;
; #pragma unroll
;                 for (int bj = 0; bj < 2; ++bj) {
;                     const size_t off = (size_t)row * DM + colbase + 32 * bj;
;                     f32x4 h0 = hv[m][bj][0], h1 = hv[m][bj][1];
;                     const u32x4 p4 = pw[m][bj];
;                     const f32x4 a0 = acc[ai][bj][m][0], a1 = acc[ai][bj][m][1];
;                     h0.x += bflo(p4.x) * __builtin_amdgcn_rcpf(1.0f + __builtin_amdgcn_exp2f(a0.x * rs));
;                     h0.y += bfhi(p4.x) * __builtin_amdgcn_rcpf(1.0f + __builtin_amdgcn_exp2f(a0.y * rs));
;                     h0.z += bflo(p4.y) * __builtin_amdgcn_rcpf(1.0f + __builtin_amdgcn_exp2f(a0.z * rs));
;                     h0.w += bfhi(p4.y) * __builtin_amdgcn_rcpf(1.0f + __builtin_amdgcn_exp2f(a0.w * rs));
;                     h1.x += bflo(p4.z) * __builtin_amdgcn_rcpf(1.0f + __builtin_amdgcn_exp2f(a1.x * rs));
;                     h1.y += bfhi(p4.z) * __builtin_amdgcn_rcpf(1.0f + __builtin_amdgcn_exp2f(a1.y * rs));
;                     h1.z += bflo(p4.w) * __builtin_amdgcn_rcpf(1.0f + __builtin_amdgcn_exp2f(a1.z * rs));
;                     h1.w += bfhi(p4.w) * __builtin_amdgcn_rcpf(1.0f + __builtin_amdgcn_exp2f(a1.w * rs));
;                     *(f32x4*)(out + off) = h0; *(f32x4*)(out + off + 4) = h1;
	v_rcp_f32_e32 v113, v113
	flat_store_dwordx4 v[206:207], v[120:123] offset:16
	flat_store_dwordx4 v[206:207], v[124:127]
	v_mul_f32_e32 v114, v114, v212
	v_lshlrev_b32_e32 v120, 16, v214
	v_and_b32_e32 v121, 0xffff0000, v214
	v_lshlrev_b32_e32 v122, 16, v218
	v_and_b32_e32 v123, 0xffff0000, v218
	v_pk_fma_f32 v[116:117], v[116:117], v[122:123], v[120:121]
	v_lshlrev_b32_e32 v120, 16, v215
	v_and_b32_e32 v121, 0xffff0000, v215
	v_lshlrev_b32_e32 v122, 16, v219
	v_and_b32_e32 v123, 0xffff0000, v219
	v_pk_fma_f32 v[118:119], v[118:119], v[122:123], v[120:121]
	v_lshlrev_b32_e32 v120, 16, v216
	v_and_b32_e32 v121, 0xffff0000, v216
	v_lshlrev_b32_e32 v122, 16, v220
	v_and_b32_e32 v123, 0xffff0000, v220
	v_pk_fma_f32 v[112:113], v[112:113], v[122:123], v[120:121]
	v_fmamk_f32 v123, v234, 0x3a000000, v205
	v_mul_f32_e32 v124, 0x4b800000, v123
	v_cmp_gt_f32_e32 vcc, s40, v123
	flat_store_dwordx4 v[206:207], v[116:119] offset:128
	v_mul_f32_e32 v115, v115, v212
	v_cndmask_b32_e32 v123, v123, v124, vcc
	v_rsq_f32_e32 v124, v123
	v_exp_f32_e32 v114, v114
	v_exp_f32_e32 v115, v115
	v_lshlrev_b32_e32 v120, 16, v217
	v_mul_f32_e32 v116, 0x45800000, v124
	v_cndmask_b32_e32 v116, v124, v116, vcc
	v_mul_f32_e32 v116, 0xbfb8aa3b, v116
	v_mul_f32_e32 v108, v108, v116
	v_mul_f32_e32 v109, v109, v116
	v_exp_f32_e32 v108, v108
	v_exp_f32_e32 v109, v109
	v_mul_f32_e32 v110, v110, v116
	v_mul_f32_e32 v111, v111, v116
	v_exp_f32_e32 v110, v110
	v_exp_f32_e32 v111, v111
	v_mul_f32_e32 v104, v104, v116
	v_mul_f32_e32 v105, v105, v116
	v_add_f32_e32 v114, 1.0, v114
	v_add_f32_e32 v115, 1.0, v115
	v_exp_f32_e32 v104, v104
	v_exp_f32_e32 v105, v105
	v_mul_f32_e32 v106, v106, v116
	v_mul_f32_e32 v107, v107, v116
	v_rcp_f32_e32 v114, v114
	v_rcp_f32_e32 v115, v115
	v_exp_f32_e32 v106, v106
	v_exp_f32_e32 v107, v107
	v_add_f32_e32 v108, 1.0, v108
	v_add_f32_e32 v109, 1.0, v109
	v_mul_f32_e32 v100, v100, v116
	v_mul_f32_e32 v101, v101, v116
	v_rcp_f32_e32 v108, v108
	v_rcp_f32_e32 v109, v109
	v_add_f32_e32 v110, 1.0, v110
	v_add_f32_e32 v111, 1.0, v111
	v_exp_f32_e32 v100, v100
	v_exp_f32_e32 v101, v101
	v_mul_f32_e32 v102, v102, v116
	v_mul_f32_e32 v103, v103, v116
	v_and_b32_e32 v121, 0xffff0000, v217
	v_lshlrev_b32_e32 v122, 16, v221
	v_and_b32_e32 v123, 0xffff0000, v221
	v_rcp_f32_e32 v110, v110
	v_rcp_f32_e32 v111, v111
	v_add_f32_e32 v104, 1.0, v104
	v_add_f32_e32 v105, 1.0, v105
	v_exp_f32_e32 v102, v102
	v_exp_f32_e32 v103, v103
	v_mul_f32_e32 v96, v96, v116
	v_mul_f32_e32 v97, v97, v116
	v_pk_fma_f32 v[114:115], v[114:115], v[122:123], v[120:121]
	v_rcp_f32_e32 v104, v104
	v_rcp_f32_e32 v105, v105
	v_add_f32_e32 v106, 1.0, v106
	v_add_f32_e32 v107, 1.0, v107
	v_exp_f32_e32 v96, v96
	v_exp_f32_e32 v97, v97
	flat_store_dwordx4 v[206:207], v[112:115] offset:144
	v_rcp_f32_e32 v106, v106
	v_rcp_f32_e32 v107, v107
	v_lshlrev_b32_e32 v112, 16, v172
	v_and_b32_e32 v113, 0xffff0000, v172
	v_lshlrev_b32_e32 v114, 16, v168
	v_and_b32_e32 v115, 0xffff0000, v168
	v_pk_fma_f32 v[108:109], v[108:109], v[114:115], v[112:113]
	v_lshlrev_b32_e32 v112, 16, v173
	v_and_b32_e32 v113, 0xffff0000, v173
	v_lshlrev_b32_e32 v114, 16, v169
	v_and_b32_e32 v115, 0xffff0000, v169
	v_add_f32_e32 v100, 1.0, v100
	v_add_f32_e32 v101, 1.0, v101
	v_pk_fma_f32 v[110:111], v[110:111], v[114:115], v[112:113]
	v_lshlrev_b32_e32 v112, 16, v174
	v_and_b32_e32 v113, 0xffff0000, v174
	v_lshlrev_b32_e32 v114, 16, v170
	v_and_b32_e32 v115, 0xffff0000, v170
	v_rcp_f32_e32 v100, v100
	v_rcp_f32_e32 v101, v101
	v_add_f32_e32 v102, 1.0, v102
	v_add_f32_e32 v103, 1.0, v103
	v_pk_fma_f32 v[104:105], v[104:105], v[114:115], v[112:113]
	v_lshlrev_b32_e32 v112, 16, v175
	v_and_b32_e32 v113, 0xffff0000, v175
	v_lshlrev_b32_e32 v114, 16, v171
	v_and_b32_e32 v115, 0xffff0000, v171
	v_rcp_f32_e32 v102, v102
	v_rcp_f32_e32 v103, v103
	v_add_f32_e32 v96, 1.0, v96
	v_add_f32_e32 v97, 1.0, v97
	v_pk_fma_f32 v[106:107], v[106:107], v[114:115], v[112:113]
	v_lshl_add_u64 v[112:113], v[198:199], 2, s[2:3]
	v_rcp_f32_e32 v96, v96
	v_rcp_f32_e32 v97, v97
	flat_store_dwordx4 v[112:113], v[104:107] offset:16
	flat_store_dwordx4 v[112:113], v[108:111]
	v_mul_f32_e32 v98, v98, v116
	v_lshlrev_b32_e32 v104, 16, v164
	v_and_b32_e32 v105, 0xffff0000, v164
	v_lshlrev_b32_e32 v106, 16, v160
	v_and_b32_e32 v107, 0xffff0000, v160
	v_pk_fma_f32 v[100:101], v[100:101], v[106:107], v[104:105]
	v_lshlrev_b32_e32 v104, 16, v165
	v_and_b32_e32 v105, 0xffff0000, v165
	v_lshlrev_b32_e32 v106, 16, v161
	v_and_b32_e32 v107, 0xffff0000, v161
	v_pk_fma_f32 v[102:103], v[102:103], v[106:107], v[104:105]
	v_lshlrev_b32_e32 v104, 16, v166
	v_and_b32_e32 v105, 0xffff0000, v166
	v_lshlrev_b32_e32 v106, 16, v162
	v_and_b32_e32 v107, 0xffff0000, v162
	v_pk_fma_f32 v[96:97], v[96:97], v[106:107], v[104:105]
	v_fmamk_f32 v107, v235, 0x3a000000, v205
	v_mul_f32_e32 v108, 0x4b800000, v107
	v_cmp_gt_f32_e32 vcc, s40, v107
	flat_store_dwordx4 v[112:113], v[100:103] offset:128
	v_mul_f32_e32 v99, v99, v116
	v_cndmask_b32_e32 v107, v107, v108, vcc
	v_rsq_f32_e32 v108, v107
	v_exp_f32_e32 v98, v98
	v_exp_f32_e32 v99, v99
	v_lshlrev_b32_e32 v104, 16, v167
	v_mul_f32_e32 v100, 0x45800000, v108
	v_cndmask_b32_e32 v100, v108, v100, vcc
	v_mul_f32_e32 v100, 0xbfb8aa3b, v100
	v_mul_f32_e32 v92, v92, v100
	v_mul_f32_e32 v93, v93, v100
	v_exp_f32_e32 v92, v92
	v_exp_f32_e32 v93, v93
	v_mul_f32_e32 v94, v94, v100
	v_mul_f32_e32 v95, v95, v100
	v_exp_f32_e32 v94, v94
	v_exp_f32_e32 v95, v95
	v_mul_f32_e32 v88, v88, v100
	v_mul_f32_e32 v89, v89, v100
	v_add_f32_e32 v98, 1.0, v98
	v_add_f32_e32 v99, 1.0, v99
	v_exp_f32_e32 v88, v88
	v_exp_f32_e32 v89, v89
	v_mul_f32_e32 v90, v90, v100
; __device__ __forceinline__ float bflo(unsigned u) { return __uint_as_float(u << 16); }
; __device__ __forceinline__ float bfhi(unsigned u) { return __uint_as_float(u & 0xffff0000u); }
;     __device__ __forceinline__ void operator()(const Acc& acc, const Unit& u, int wr, int wc, int fr, int fq) const {
;     ...
;             for (int m = 0; m < 4; ++m) {
;                 const int row = u.pm * 256 + ai * 128 + wr * 64 + m * 16 + fr;
;                 const float rs = rsqrtf(rsv[m] * (1.0f / DM) + EPS) * -1.4426950408889634f;
; #pragma unroll
;                 for (int bj = 0; bj < 2; ++bj) {
;                     const size_t off = (size_t)row * DM + colbase + 32 * bj;
;                     f32x4 h0 = hv[m][bj][0], h1 = hv[m][bj][1];
;                     const u32x4 p4 = pw[m][bj];
;                     const f32x4 a0 = acc[ai][bj][m][0], a1 = acc[ai][bj][m][1];
;                     h0.x += bflo(p4.x) * __builtin_amdgcn_rcpf(1.0f + __builtin_amdgcn_exp2f(a0.x * rs));
;                     h0.y += bfhi(p4.x) * __builtin_amdgcn_rcpf(1.0f + __builtin_amdgcn_exp2f(a0.y * rs));
;                     h0.z += bflo(p4.y) * __builtin_amdgcn_rcpf(1.0f + __builtin_amdgcn_exp2f(a0.z * rs));
;                     h0.w += bfhi(p4.y) * __builtin_amdgcn_rcpf(1.0f + __builtin_amdgcn_exp2f(a0.w * rs));
;                     h1.x += bflo(p4.z) * __builtin_amdgcn_rcpf(1.0f + __builtin_amdgcn_exp2f(a1.x * rs));
;                     h1.y += bfhi(p4.z) * __builtin_amdgcn_rcpf(1.0f + __builtin_amdgcn_exp2f(a1.y * rs));
;                     h1.z += bflo(p4.w) * __builtin_amdgcn_rcpf(1.0f + __builtin_amdgcn_exp2f(a1.z * rs));
;                     h1.w += bfhi(p4.w) * __builtin_amdgcn_rcpf(1.0f + __builtin_amdgcn_exp2f(a1.w * rs));
;                     *(f32x4*)(out + off) = h0; *(f32x4*)(out + off + 4) = h1;
	v_mul_f32_e32 v91, v91, v100
	v_rcp_f32_e32 v98, v98
	v_rcp_f32_e32 v99, v99
	v_exp_f32_e32 v90, v90
	v_exp_f32_e32 v91, v91
	v_add_f32_e32 v92, 1.0, v92
	v_add_f32_e32 v93, 1.0, v93
	v_mul_f32_e32 v84, v84, v100
	v_mul_f32_e32 v85, v85, v100
	v_rcp_f32_e32 v92, v92
	v_rcp_f32_e32 v93, v93
	v_add_f32_e32 v94, 1.0, v94
	v_add_f32_e32 v95, 1.0, v95
	v_exp_f32_e32 v84, v84
	v_exp_f32_e32 v85, v85
	v_mul_f32_e32 v86, v86, v100
	v_mul_f32_e32 v87, v87, v100
	v_and_b32_e32 v105, 0xffff0000, v167
	v_lshlrev_b32_e32 v106, 16, v163
	v_and_b32_e32 v107, 0xffff0000, v163
	v_rcp_f32_e32 v94, v94
	v_rcp_f32_e32 v95, v95
	v_add_f32_e32 v88, 1.0, v88
	v_add_f32_e32 v89, 1.0, v89
	v_exp_f32_e32 v86, v86
	v_exp_f32_e32 v87, v87
	v_mul_f32_e32 v80, v80, v100
	v_mul_f32_e32 v81, v81, v100
	v_pk_fma_f32 v[98:99], v[98:99], v[106:107], v[104:105]
	v_rcp_f32_e32 v88, v88
	v_rcp_f32_e32 v89, v89
	v_add_f32_e32 v90, 1.0, v90
	v_add_f32_e32 v91, 1.0, v91
	v_exp_f32_e32 v80, v80
	v_exp_f32_e32 v81, v81
	flat_store_dwordx4 v[112:113], v[96:99] offset:144
	v_rcp_f32_e32 v90, v90
	v_rcp_f32_e32 v91, v91
	v_lshlrev_b32_e32 v96, 16, v156
	v_and_b32_e32 v97, 0xffff0000, v156
	v_lshlrev_b32_e32 v98, 16, v152
	v_and_b32_e32 v99, 0xffff0000, v152
	v_pk_fma_f32 v[92:93], v[92:93], v[98:99], v[96:97]
	v_lshlrev_b32_e32 v96, 16, v157
	v_and_b32_e32 v97, 0xffff0000, v157
	v_lshlrev_b32_e32 v98, 16, v153
	v_and_b32_e32 v99, 0xffff0000, v153
	v_add_f32_e32 v84, 1.0, v84
	v_add_f32_e32 v85, 1.0, v85
	v_pk_fma_f32 v[94:95], v[94:95], v[98:99], v[96:97]
	v_lshlrev_b32_e32 v96, 16, v158
	v_and_b32_e32 v97, 0xffff0000, v158
	v_lshlrev_b32_e32 v98, 16, v154
	v_and_b32_e32 v99, 0xffff0000, v154
	v_rcp_f32_e32 v84, v84
	v_rcp_f32_e32 v85, v85
	v_add_f32_e32 v86, 1.0, v86
	v_add_f32_e32 v87, 1.0, v87
	v_pk_fma_f32 v[88:89], v[88:89], v[98:99], v[96:97]
	v_lshlrev_b32_e32 v96, 16, v159
	v_and_b32_e32 v97, 0xffff0000, v159
	v_lshlrev_b32_e32 v98, 16, v155
	v_and_b32_e32 v99, 0xffff0000, v155
	v_rcp_f32_e32 v86, v86
	v_rcp_f32_e32 v87, v87
	v_add_f32_e32 v80, 1.0, v80
	v_add_f32_e32 v81, 1.0, v81
	v_pk_fma_f32 v[90:91], v[90:91], v[98:99], v[96:97]
	v_lshl_add_u64 v[96:97], v[196:197], 2, s[2:3]
	v_rcp_f32_e32 v80, v80
	v_rcp_f32_e32 v81, v81
	flat_store_dwordx4 v[96:97], v[88:91] offset:16
	flat_store_dwordx4 v[96:97], v[92:95]
	v_mul_f32_e32 v82, v82, v100
	v_lshlrev_b32_e32 v88, 16, v148
	v_and_b32_e32 v89, 0xffff0000, v148
	v_lshlrev_b32_e32 v90, 16, v144
	v_and_b32_e32 v91, 0xffff0000, v144
	v_pk_fma_f32 v[84:85], v[84:85], v[90:91], v[88:89]
	v_lshlrev_b32_e32 v88, 16, v149
	v_and_b32_e32 v89, 0xffff0000, v149
	v_lshlrev_b32_e32 v90, 16, v145
	v_and_b32_e32 v91, 0xffff0000, v145
	v_pk_fma_f32 v[86:87], v[86:87], v[90:91], v[88:89]
	v_lshlrev_b32_e32 v88, 16, v150
	v_and_b32_e32 v89, 0xffff0000, v150
	v_lshlrev_b32_e32 v90, 16, v146
	v_and_b32_e32 v91, 0xffff0000, v146
	v_pk_fma_f32 v[80:81], v[80:81], v[90:91], v[88:89]
	v_fmamk_f32 v91, v191, 0x3a000000, v205
	v_mul_f32_e32 v92, 0x4b800000, v91
	v_cmp_gt_f32_e32 vcc, s40, v91
	flat_store_dwordx4 v[96:97], v[84:87] offset:128
	v_mul_f32_e32 v83, v83, v100
	v_cndmask_b32_e32 v91, v91, v92, vcc
	v_rsq_f32_e32 v92, v91
	v_exp_f32_e32 v82, v82
	v_exp_f32_e32 v83, v83
	v_lshlrev_b32_e32 v88, 16, v151
	v_mul_f32_e32 v84, 0x45800000, v92
	v_cndmask_b32_e32 v84, v92, v84, vcc
	v_mul_f32_e32 v84, 0xbfb8aa3b, v84
	v_mul_f32_e32 v76, v76, v84
	v_mul_f32_e32 v77, v77, v84
	v_exp_f32_e32 v76, v76
	v_exp_f32_e32 v77, v77
	v_mul_f32_e32 v78, v78, v84
	v_mul_f32_e32 v79, v79, v84
	v_exp_f32_e32 v78, v78
	v_exp_f32_e32 v79, v79
	v_mul_f32_e32 v72, v72, v84
	v_mul_f32_e32 v73, v73, v84
	v_add_f32_e32 v82, 1.0, v82
	v_add_f32_e32 v83, 1.0, v83
	v_exp_f32_e32 v72, v72
	v_exp_f32_e32 v73, v73
	v_mul_f32_e32 v74, v74, v84
	v_mul_f32_e32 v75, v75, v84
	v_rcp_f32_e32 v82, v82
	v_rcp_f32_e32 v83, v83
	v_exp_f32_e32 v74, v74
	v_exp_f32_e32 v75, v75
	v_add_f32_e32 v76, 1.0, v76
	v_add_f32_e32 v77, 1.0, v77
	v_mul_f32_e32 v68, v68, v84
	v_mul_f32_e32 v69, v69, v84
	v_rcp_f32_e32 v76, v76
	v_rcp_f32_e32 v77, v77
	v_add_f32_e32 v78, 1.0, v78
	v_add_f32_e32 v79, 1.0, v79
	v_exp_f32_e32 v68, v68
	v_exp_f32_e32 v69, v69
	v_mul_f32_e32 v70, v70, v84
	v_mul_f32_e32 v71, v71, v84
	v_and_b32_e32 v89, 0xffff0000, v151
	v_lshlrev_b32_e32 v90, 16, v147
	v_and_b32_e32 v91, 0xffff0000, v147
	v_rcp_f32_e32 v78, v78
	v_rcp_f32_e32 v79, v79
; __device__ __forceinline__ float bflo(unsigned u) { return __uint_as_float(u << 16); }
;     __device__ __forceinline__ void operator()(const Acc& acc, const Unit& u, int wr, int wc, int fr, int fq) const {
;     ...
;             for (int m = 0; m < 4; ++m) { const int row = u.pm * 256 + ai * 128 + wr * 64 + m * 16 + fr; const size_t off = (size_t)row * DM + colbase;
;                 rsv[m] = rowss[row];
; #pragma unroll
;                 for (int bj = 0; bj < 2; ++bj) { const u32x4 hw = __builtin_nontemporal_load((const u32x4*)(hin + off + 32 * bj));
;                     hv[m][bj][0] = (f32x4){bflo(hw.x), bfhi(hw.x), bflo(hw.y), bfhi(hw.y)}; hv[m][bj][1] = (f32x4){bflo(hw.z), bfhi(hw.z), bflo(hw.w), bfhi(hw.w)};
;                     pw[m][bj] = __builtin_nontemporal_load((const u32x4*)(PP + off + 32 * bj)); } }
; #pragma unroll
;             for (int m = 0; m < 4; ++m) {
;                 const int row = u.pm * 256 + ai * 128 + wr * 64 + m * 16 + fr;
;                 const float rs = rsqrtf(rsv[m] * (1.0f / DM) + EPS) * -1.4426950408889634f;
; #pragma unroll
;                 for (int bj = 0; bj < 2; ++bj) {
;                     const size_t off = (size_t)row * DM + colbase + 32 * bj;
;                     f32x4 h0 = hv[m][bj][0], h1 = hv[m][bj][1];
;                     const u32x4 p4 = pw[m][bj];
;                     const f32x4 a0 = acc[ai][bj][m][0], a1 = acc[ai][bj][m][1];
;                     h0.x += bflo(p4.x) * __builtin_amdgcn_rcpf(1.0f + __builtin_amdgcn_exp2f(a0.x * rs));
;                     h0.y += bfhi(p4.x) * __builtin_amdgcn_rcpf(1.0f + __builtin_amdgcn_exp2f(a0.y * rs));
;                     h0.z += bflo(p4.y) * __builtin_amdgcn_rcpf(1.0f + __builtin_amdgcn_exp2f(a0.z * rs));
;                     h0.w += bfhi(p4.y) * __builtin_amdgcn_rcpf(1.0f + __builtin_amdgcn_exp2f(a0.w * rs));
;                     h1.x += bflo(p4.z) * __builtin_amdgcn_rcpf(1.0f + __builtin_amdgcn_exp2f(a1.x * rs));
;                     h1.y += bfhi(p4.z) * __builtin_amdgcn_rcpf(1.0f + __builtin_amdgcn_exp2f(a1.y * rs));
;                     h1.z += bflo(p4.w) * __builtin_amdgcn_rcpf(1.0f + __builtin_amdgcn_exp2f(a1.z * rs));
;                     h1.w += bfhi(p4.w) * __builtin_amdgcn_rcpf(1.0f + __builtin_amdgcn_exp2f(a1.w * rs));
;                     *(f32x4*)(out + off) = h0; *(f32x4*)(out + off + 4) = h1;
	v_add_f32_e32 v72, 1.0, v72
	v_add_f32_e32 v73, 1.0, v73
	v_exp_f32_e32 v70, v70
	v_exp_f32_e32 v71, v71
	v_mul_f32_e32 v64, v64, v84
	v_mul_f32_e32 v65, v65, v84
	v_pk_fma_f32 v[82:83], v[82:83], v[90:91], v[88:89]
	v_rcp_f32_e32 v72, v72
	v_rcp_f32_e32 v73, v73
	v_add_f32_e32 v74, 1.0, v74
	v_add_f32_e32 v75, 1.0, v75
	v_exp_f32_e32 v64, v64
	v_exp_f32_e32 v65, v65
	v_mul_f32_e32 v66, v66, v84
	v_mul_f32_e32 v67, v67, v84
	flat_store_dwordx4 v[96:97], v[80:83] offset:144
	v_rcp_f32_e32 v74, v74
	v_rcp_f32_e32 v75, v75
	v_lshlrev_b32_e32 v80, 16, v140
	v_and_b32_e32 v81, 0xffff0000, v140
	v_lshlrev_b32_e32 v82, 16, v136
	v_and_b32_e32 v83, 0xffff0000, v136
	v_exp_f32_e32 v66, v66
	v_exp_f32_e32 v67, v67
	v_pk_fma_f32 v[76:77], v[76:77], v[82:83], v[80:81]
	v_lshlrev_b32_e32 v80, 16, v141
	v_and_b32_e32 v81, 0xffff0000, v141
	v_lshlrev_b32_e32 v82, 16, v137
	v_and_b32_e32 v83, 0xffff0000, v137
	v_add_f32_e32 v68, 1.0, v68
	v_add_f32_e32 v69, 1.0, v69
	v_pk_fma_f32 v[78:79], v[78:79], v[82:83], v[80:81]
	v_lshlrev_b32_e32 v80, 16, v142
	v_and_b32_e32 v81, 0xffff0000, v142
	v_lshlrev_b32_e32 v82, 16, v138
	v_and_b32_e32 v83, 0xffff0000, v138
	v_rcp_f32_e32 v68, v68
	v_rcp_f32_e32 v69, v69
	v_add_f32_e32 v70, 1.0, v70
	v_add_f32_e32 v71, 1.0, v71
	v_pk_fma_f32 v[72:73], v[72:73], v[82:83], v[80:81]
	v_lshlrev_b32_e32 v80, 16, v143
	v_and_b32_e32 v81, 0xffff0000, v143
	v_lshlrev_b32_e32 v82, 16, v139
	v_and_b32_e32 v83, 0xffff0000, v139
	v_rcp_f32_e32 v70, v70
	v_rcp_f32_e32 v71, v71
	v_add_f32_e32 v64, 1.0, v64
	v_add_f32_e32 v65, 1.0, v65
	v_pk_fma_f32 v[74:75], v[74:75], v[82:83], v[80:81]
	v_lshl_add_u64 v[80:81], v[194:195], 2, s[2:3]
	v_rcp_f32_e32 v64, v64
	v_rcp_f32_e32 v65, v65
	v_add_f32_e32 v66, 1.0, v66
	v_add_f32_e32 v67, 1.0, v67
	flat_store_dwordx4 v[80:81], v[72:75] offset:16
	v_rcp_f32_e32 v66, v66
	v_rcp_f32_e32 v67, v67
	v_lshlrev_b32_e32 v72, 16, v132
	v_and_b32_e32 v73, 0xffff0000, v132
	v_lshlrev_b32_e32 v74, 16, v128
	v_and_b32_e32 v75, 0xffff0000, v128
	v_pk_fma_f32 v[68:69], v[68:69], v[74:75], v[72:73]
	v_lshlrev_b32_e32 v72, 16, v133
	v_and_b32_e32 v73, 0xffff0000, v133
	v_lshlrev_b32_e32 v74, 16, v129
	v_and_b32_e32 v75, 0xffff0000, v129
	v_pk_fma_f32 v[70:71], v[70:71], v[74:75], v[72:73]
	v_lshlrev_b32_e32 v72, 16, v134
	v_and_b32_e32 v73, 0xffff0000, v134
	v_lshlrev_b32_e32 v74, 16, v130
	v_and_b32_e32 v75, 0xffff0000, v130
	v_pk_fma_f32 v[64:65], v[64:65], v[74:75], v[72:73]
	v_lshlrev_b32_e32 v72, 16, v135
	v_and_b32_e32 v73, 0xffff0000, v135
	v_lshlrev_b32_e32 v74, 16, v131
	v_and_b32_e32 v75, 0xffff0000, v131
	flat_store_dwordx4 v[80:81], v[76:79]
	v_pk_fma_f32 v[66:67], v[66:67], v[74:75], v[72:73]
	flat_store_dwordx4 v[80:81], v[68:71] offset:128
	flat_store_dwordx4 v[80:81], v[64:67] offset:144
	global_load_dword v68, v[192:193], off offset:512
	s_nop 0
	v_add_u32_e32 v64, 0x80, v190
	v_ashrrev_i32_e32 v65, 31, v64
	v_lshlrev_b64 v[64:65], 11, v[64:65]
	v_lshl_add_u64 v[136:137], v[64:65], 0, v[188:189]
	v_lshlrev_b64 v[64:65], 1, v[136:137]
	v_lshl_add_u64 v[66:67], s[6:7], 0, v[64:65]
	v_lshl_add_u64 v[64:65], s[8:9], 0, v[64:65]
	v_mov_b64_e32 v[124:125], v[248:249]
	v_mov_b64_e32 v[126:127], v[252:253]
	global_load_dwordx4 v[128:131], v[64:65], off nt
	v_mov_b64_e32 v[132:133], v[236:237]
	v_mov_b64_e32 v[134:135], v[238:239]
	global_load_dwordx4 v[112:115], v[64:65], off offset:64 nt
	v_add_u32_e32 v64, 0x90, v190
	v_ashrrev_i32_e32 v65, 31, v64
	v_lshlrev_b64 v[64:65], 11, v[64:65]
	v_lshl_add_u64 v[120:121], v[64:65], 0, v[188:189]
	v_lshlrev_b64 v[64:65], 1, v[120:121]
	v_lshl_add_u64 v[66:67], s[6:7], 0, v[64:65]
	v_lshl_add_u64 v[64:65], s[8:9], 0, v[64:65]
	v_mov_b64_e32 v[108:109], v[240:241]
	v_mov_b64_e32 v[110:111], v[250:251]
	v_mov_b32_e32 v100, 0x20000
	v_lshl_add_u32 v100, v200, 4, v100
	v_lshl_add_u32 v100, s79, 6, v100
	v_lshl_add_u32 v100, s86, 4, v100
	ds_read_b128 v[100:103], v100
	global_load_dwordx4 v[104:107], v[64:65], off nt
	global_load_dwordx4 v[96:99], v[64:65], off offset:64 nt
	v_add_u32_e32 v64, 0xa0, v190
	v_ashrrev_i32_e32 v65, 31, v64
	v_lshlrev_b64 v[64:65], 11, v[64:65]
	v_lshl_add_u64 v[118:119], v[64:65], 0, v[188:189]
	v_lshlrev_b64 v[64:65], 1, v[118:119]
	v_lshl_add_u64 v[66:67], s[6:7], 0, v[64:65]
	v_lshl_add_u64 v[64:65], s[8:9], 0, v[64:65]
	s_cmp_eq_u32 s79, 64
	s_cbranch_scc0 .Lhbk_r
	s_cmp_eq_u32 s86, 0xc0
	s_cbranch_scc1 .Lhbk_rl

; __device__ __forceinline__ float bflo(unsigned u) { return __uint_as_float(u << 16); }
;     __device__ __forceinline__ void operator()(const Acc& acc, const Unit& u, int wr, int wc, int fr, int fq) const {
;     ...
;             for (int m = 0; m < 4; ++m) { const int row = u.pm * 256 + ai * 128 + wr * 64 + m * 16 + fr; const size_t off = (size_t)row * DM + colbase;
;                 rsv[m] = rowss[row];
; #pragma unroll
;                 for (int bj = 0; bj < 2; ++bj) { const u32x4 hw = __builtin_nontemporal_load((const u32x4*)(hin + off + 32 * bj));
;                     hv[m][bj][0] = (f32x4){bflo(hw.x), bfhi(hw.x), bflo(hw.y), bfhi(hw.y)}; hv[m][bj][1] = (f32x4){bflo(hw.z), bfhi(hw.z), bflo(hw.w), bfhi(hw.w)};
;                     pw[m][bj] = __builtin_nontemporal_load((const u32x4*)(PP + off + 32 * bj)); } }
; #pragma unroll
;             for (int m = 0; m < 4; ++m) {
;                 const int row = u.pm * 256 + ai * 128 + wr * 64 + m * 16 + fr;
;                 const float rs = rsqrtf(rsv[m] * (1.0f / DM) + EPS) * -1.4426950408889634f;
; #pragma unroll
;                 for (int bj = 0; bj < 2; ++bj) {
;                     const size_t off = (size_t)row * DM + colbase + 32 * bj;
;                     f32x4 h0 = hv[m][bj][0], h1 = hv[m][bj][1];
;                     const u32x4 p4 = pw[m][bj];
;                     const f32x4 a0 = acc[ai][bj][m][0], a1 = acc[ai][bj][m][1];
;                     h0.x += bflo(p4.x) * __builtin_amdgcn_rcpf(1.0f + __builtin_amdgcn_exp2f(a0.x * rs));
;                     h0.y += bfhi(p4.x) * __builtin_amdgcn_rcpf(1.0f + __builtin_amdgcn_exp2f(a0.y * rs));
;                     h0.z += bflo(p4.y) * __builtin_amdgcn_rcpf(1.0f + __builtin_amdgcn_exp2f(a0.z * rs));
;                     h0.w += bfhi(p4.y) * __builtin_amdgcn_rcpf(1.0f + __builtin_amdgcn_exp2f(a0.w * rs));
;                     h1.x += bflo(p4.z) * __builtin_amdgcn_rcpf(1.0f + __builtin_amdgcn_exp2f(a1.x * rs));
;                     h1.y += bfhi(p4.z) * __builtin_amdgcn_rcpf(1.0f + __builtin_amdgcn_exp2f(a1.y * rs));
;                     h1.z += bflo(p4.w) * __builtin_amdgcn_rcpf(1.0f + __builtin_amdgcn_exp2f(a1.z * rs));
;                     h1.w += bfhi(p4.w) * __builtin_amdgcn_rcpf(1.0f + __builtin_amdgcn_exp2f(a1.w * rs));
;                     *(f32x4*)(out + off) = h0; *(f32x4*)(out + off + 4) = h1;
.Lhbk_rl:
	global_load_dwordx4 v[92:95], v[66:67], off nt
.Lhbk_rd:
	global_load_dwordx4 v[84:87], v[66:67], off offset:64 nt
	global_load_dwordx4 v[88:91], v[64:65], off nt
	global_load_dwordx4 v[80:83], v[64:65], off offset:64 nt
	global_load_dword v123, v[192:193], off offset:576
	global_load_dword v142, v[192:193], off offset:640
	global_load_dword v122, v[192:193], off offset:704
	v_add_u32_e32 v64, 0xb0, v190
	v_ashrrev_i32_e32 v65, 31, v64
	v_lshlrev_b64 v[64:65], 11, v[64:65]
	v_lshl_add_u64 v[116:117], v[64:65], 0, v[188:189]
	v_lshlrev_b64 v[64:65], 1, v[116:117]
	v_lshl_add_u64 v[66:67], s[6:7], 0, v[64:65]
	s_waitcnt vmcnt(0) lgkmcnt(0)
	v_fmamk_f32 v68, v68, 0x3a000000, v205
	v_mul_f32_e32 v69, 0x4b800000, v68
	v_cmp_gt_f32_e32 vcc, s40, v68
	v_lshlrev_b32_e32 v140, 16, v128
	s_nop 0
	v_cndmask_b32_e32 v68, v68, v69, vcc
	v_rsq_f32_e32 v70, v68
	v_lshl_add_u64 v[68:69], s[8:9], 0, v[64:65]
	v_lshlrev_b32_e32 v138, 16, v124
	v_and_b32_e32 v139, 0xffff0000, v124
	v_mul_f32_e32 v71, 0x45800000, v70
	v_cndmask_b32_e32 v70, v70, v71, vcc
	v_mul_f32_e32 v143, 0xbfb8aa3b, v70
	v_mul_f32_e32 v62, v62, v143
	v_mul_f32_e32 v63, v63, v143
	v_exp_f32_e32 v62, v62
	v_exp_f32_e32 v63, v63
	v_mul_f32_e32 v56, v56, v143
	v_mul_f32_e32 v57, v57, v143
	v_exp_f32_e32 v56, v56
	v_exp_f32_e32 v57, v57
	v_mul_f32_e32 v58, v58, v143
	v_mul_f32_e32 v59, v59, v143
	v_exp_f32_e32 v58, v58
	v_exp_f32_e32 v59, v59
	v_mul_f32_e32 v52, v52, v143
	v_mul_f32_e32 v53, v53, v143
	v_add_f32_e32 v62, 1.0, v62
	v_add_f32_e32 v63, 1.0, v63
	v_exp_f32_e32 v52, v52
	v_exp_f32_e32 v53, v53
	v_mul_f32_e32 v54, v54, v143
	v_mul_f32_e32 v55, v55, v143
	v_mul_f32_e32 v60, v60, v143
	v_mul_f32_e32 v61, v61, v143
	v_rcp_f32_e32 v62, v62
	v_rcp_f32_e32 v63, v63
	v_add_f32_e32 v56, 1.0, v56
	v_add_f32_e32 v57, 1.0, v57
	v_exp_f32_e32 v54, v54
	v_exp_f32_e32 v55, v55
	v_mul_f32_e32 v48, v48, v143
	v_mul_f32_e32 v49, v49, v143
	v_exp_f32_e32 v60, v60
	v_exp_f32_e32 v61, v61
	v_rcp_f32_e32 v56, v56
	v_rcp_f32_e32 v57, v57
	v_add_f32_e32 v58, 1.0, v58
	v_add_f32_e32 v59, 1.0, v59
	v_exp_f32_e32 v48, v48
	v_exp_f32_e32 v49, v49
	v_rcp_f32_e32 v58, v58
	v_rcp_f32_e32 v59, v59
	v_and_b32_e32 v141, 0xffff0000, v128
	v_lshlrev_b32_e32 v124, 16, v125
	v_and_b32_e32 v125, 0xffff0000, v125
	v_lshlrev_b32_e32 v128, 16, v129
	v_and_b32_e32 v129, 0xffff0000, v129
	v_add_f32_e32 v52, 1.0, v52
	v_add_f32_e32 v53, 1.0, v53
	global_load_dwordx4 v[72:75], v[66:67], off nt
	s_nop 0
	global_load_dwordx4 v[64:67], v[66:67], off offset:64 nt
	s_nop 0
	global_load_dwordx4 v[76:79], v[68:69], off nt
	s_nop 0
	global_load_dwordx4 v[68:71], v[68:69], off offset:64 nt
	v_pk_fma_f32 v[62:63], v[62:63], v[128:129], v[124:125]
	v_lshlrev_b32_e32 v124, 16, v126
	v_and_b32_e32 v125, 0xffff0000, v126
	v_lshlrev_b32_e32 v128, 16, v130
	v_and_b32_e32 v129, 0xffff0000, v130
	v_rcp_f32_e32 v52, v52
	v_rcp_f32_e32 v53, v53
	v_add_f32_e32 v54, 1.0, v54
	v_add_f32_e32 v55, 1.0, v55
	v_add_f32_e32 v60, 1.0, v60
	v_add_f32_e32 v61, 1.0, v61
	v_pk_fma_f32 v[56:57], v[56:57], v[128:129], v[124:125]
	v_lshlrev_b32_e32 v124, 16, v127
	v_and_b32_e32 v125, 0xffff0000, v127
	v_lshlrev_b32_e32 v126, 16, v131
	v_and_b32_e32 v127, 0xffff0000, v131
	v_rcp_f32_e32 v54, v54
	v_rcp_f32_e32 v55, v55
	v_add_f32_e32 v48, 1.0, v48
	v_add_f32_e32 v49, 1.0, v49
	v_rcp_f32_e32 v60, v60
	v_rcp_f32_e32 v61, v61
	v_pk_fma_f32 v[58:59], v[58:59], v[126:127], v[124:125]
	v_lshl_add_u64 v[124:125], v[136:137], 2, s[2:3]
	v_rcp_f32_e32 v48, v48
	v_rcp_f32_e32 v49, v49
	flat_store_dwordx4 v[124:125], v[56:59] offset:16
	v_pk_fma_f32 v[60:61], v[60:61], v[140:141], v[138:139]
	flat_store_dwordx4 v[124:125], v[60:63]
	v_lshlrev_b32_e32 v56, 16, v132
	v_and_b32_e32 v57, 0xffff0000, v132
	v_lshlrev_b32_e32 v58, 16, v112
	v_and_b32_e32 v59, 0xffff0000, v112
	v_pk_fma_f32 v[52:53], v[52:53], v[58:59], v[56:57]
	v_lshlrev_b32_e32 v56, 16, v133
	v_and_b32_e32 v57, 0xffff0000, v133
	v_lshlrev_b32_e32 v58, 16, v113
	v_and_b32_e32 v59, 0xffff0000, v113
	v_pk_fma_f32 v[54:55], v[54:55], v[58:59], v[56:57]
	v_lshlrev_b32_e32 v56, 16, v134
	v_and_b32_e32 v57, 0xffff0000, v134
	v_lshlrev_b32_e32 v58, 16, v114
	v_and_b32_e32 v59, 0xffff0000, v114
	v_pk_fma_f32 v[48:49], v[48:49], v[58:59], v[56:57]
	v_fmamk_f32 v59, v123, 0x3a000000, v205
	v_mul_f32_e32 v60, 0x4b800000, v59
	v_cmp_gt_f32_e32 vcc, s40, v59
	flat_store_dwordx4 v[124:125], v[52:55] offset:128
	v_mul_f32_e32 v50, v50, v143
	v_cndmask_b32_e32 v59, v59, v60, vcc
	v_rsq_f32_e32 v60, v59
	v_mul_f32_e32 v51, v51, v143
	v_exp_f32_e32 v50, v50
	v_exp_f32_e32 v51, v51
	v_mul_f32_e32 v52, 0x45800000, v60
	v_cndmask_b32_e32 v52, v60, v52, vcc
	v_mul_f32_e32 v52, 0xbfb8aa3b, v52
	v_mul_f32_e32 v44, v44, v52
	v_mul_f32_e32 v45, v45, v52
	v_exp_f32_e32 v44, v44
	v_exp_f32_e32 v45, v45
	v_mul_f32_e32 v46, v46, v52
	v_mul_f32_e32 v47, v47, v52
	v_exp_f32_e32 v46, v46
	v_exp_f32_e32 v47, v47
	v_mul_f32_e32 v40, v40, v52
	v_mul_f32_e32 v41, v41, v52
	v_add_f32_e32 v50, 1.0, v50
	v_add_f32_e32 v51, 1.0, v51
	v_exp_f32_e32 v40, v40
	v_exp_f32_e32 v41, v41
	v_mul_f32_e32 v42, v42, v52
	v_mul_f32_e32 v43, v43, v52
	v_rcp_f32_e32 v50, v50
	v_rcp_f32_e32 v51, v51
	v_exp_f32_e32 v42, v42
	v_exp_f32_e32 v43, v43
	v_add_f32_e32 v44, 1.0, v44
	v_add_f32_e32 v45, 1.0, v45
	v_mul_f32_e32 v36, v36, v52
	v_mul_f32_e32 v37, v37, v52
	v_rcp_f32_e32 v44, v44
	v_rcp_f32_e32 v45, v45
	v_add_f32_e32 v46, 1.0, v46
	v_add_f32_e32 v47, 1.0, v47
	v_exp_f32_e32 v36, v36
	v_exp_f32_e32 v37, v37
	v_mul_f32_e32 v38, v38, v52
	v_mul_f32_e32 v39, v39, v52
	v_lshlrev_b32_e32 v56, 16, v135
	v_and_b32_e32 v57, 0xffff0000, v135
; __device__ __forceinline__ float bflo(unsigned u) { return __uint_as_float(u << 16); }
; __device__ __forceinline__ float bfhi(unsigned u) { return __uint_as_float(u & 0xffff0000u); }
;     __device__ __forceinline__ void operator()(const Acc& acc, const Unit& u, int wr, int wc, int fr, int fq) const {
;     ...
;             for (int m = 0; m < 4; ++m) {
;                 const int row = u.pm * 256 + ai * 128 + wr * 64 + m * 16 + fr;
;                 const float rs = rsqrtf(rsv[m] * (1.0f / DM) + EPS) * -1.4426950408889634f;
; #pragma unroll
;                 for (int bj = 0; bj < 2; ++bj) {
;                     const size_t off = (size_t)row * DM + colbase + 32 * bj;
;                     f32x4 h0 = hv[m][bj][0], h1 = hv[m][bj][1];
;                     const u32x4 p4 = pw[m][bj];
;                     const f32x4 a0 = acc[ai][bj][m][0], a1 = acc[ai][bj][m][1];
;                     h0.x += bflo(p4.x) * __builtin_amdgcn_rcpf(1.0f + __builtin_amdgcn_exp2f(a0.x * rs));
;                     h0.y += bfhi(p4.x) * __builtin_amdgcn_rcpf(1.0f + __builtin_amdgcn_exp2f(a0.y * rs));
;                     h0.z += bflo(p4.y) * __builtin_amdgcn_rcpf(1.0f + __builtin_amdgcn_exp2f(a0.z * rs));
;                     h0.w += bfhi(p4.y) * __builtin_amdgcn_rcpf(1.0f + __builtin_amdgcn_exp2f(a0.w * rs));
;                     h1.x += bflo(p4.z) * __builtin_amdgcn_rcpf(1.0f + __builtin_amdgcn_exp2f(a1.x * rs));
;                     h1.y += bfhi(p4.z) * __builtin_amdgcn_rcpf(1.0f + __builtin_amdgcn_exp2f(a1.y * rs));
;                     h1.z += bflo(p4.w) * __builtin_amdgcn_rcpf(1.0f + __builtin_amdgcn_exp2f(a1.z * rs));
;                     h1.w += bfhi(p4.w) * __builtin_amdgcn_rcpf(1.0f + __builtin_amdgcn_exp2f(a1.w * rs));
;                     *(f32x4*)(out + off) = h0; *(f32x4*)(out + off + 4) = h1;
	v_lshlrev_b32_e32 v58, 16, v115
	v_and_b32_e32 v59, 0xffff0000, v115
	v_rcp_f32_e32 v46, v46
	v_rcp_f32_e32 v47, v47
	v_add_f32_e32 v40, 1.0, v40
	v_add_f32_e32 v41, 1.0, v41
	v_exp_f32_e32 v38, v38
	v_exp_f32_e32 v39, v39
	v_mul_f32_e32 v32, v32, v52
	v_mul_f32_e32 v33, v33, v52
	v_pk_fma_f32 v[50:51], v[50:51], v[58:59], v[56:57]
	v_rcp_f32_e32 v40, v40
	v_rcp_f32_e32 v41, v41
	v_add_f32_e32 v42, 1.0, v42
	v_add_f32_e32 v43, 1.0, v43
	v_exp_f32_e32 v32, v32
	v_exp_f32_e32 v33, v33
	flat_store_dwordx4 v[124:125], v[48:51] offset:144
	v_rcp_f32_e32 v42, v42
	v_rcp_f32_e32 v43, v43
	v_lshlrev_b32_e32 v48, 16, v108
	v_and_b32_e32 v49, 0xffff0000, v108
	v_lshlrev_b32_e32 v50, 16, v104
	v_and_b32_e32 v51, 0xffff0000, v104
	v_pk_fma_f32 v[44:45], v[44:45], v[50:51], v[48:49]
	v_lshlrev_b32_e32 v48, 16, v109
	v_and_b32_e32 v49, 0xffff0000, v109
	v_lshlrev_b32_e32 v50, 16, v105
	v_and_b32_e32 v51, 0xffff0000, v105
	v_add_f32_e32 v36, 1.0, v36
	v_add_f32_e32 v37, 1.0, v37
	v_pk_fma_f32 v[46:47], v[46:47], v[50:51], v[48:49]
	v_lshlrev_b32_e32 v48, 16, v110
	v_and_b32_e32 v49, 0xffff0000, v110
	v_lshlrev_b32_e32 v50, 16, v106
	v_and_b32_e32 v51, 0xffff0000, v106
	v_rcp_f32_e32 v36, v36
	v_rcp_f32_e32 v37, v37
	v_add_f32_e32 v38, 1.0, v38
	v_add_f32_e32 v39, 1.0, v39
	v_pk_fma_f32 v[40:41], v[40:41], v[50:51], v[48:49]
	v_lshlrev_b32_e32 v48, 16, v111
	v_and_b32_e32 v49, 0xffff0000, v111
	v_lshlrev_b32_e32 v50, 16, v107
	v_and_b32_e32 v51, 0xffff0000, v107
	v_rcp_f32_e32 v38, v38
	v_rcp_f32_e32 v39, v39
	v_add_f32_e32 v32, 1.0, v32
	v_add_f32_e32 v33, 1.0, v33
	v_pk_fma_f32 v[42:43], v[42:43], v[50:51], v[48:49]
	v_lshl_add_u64 v[48:49], v[120:121], 2, s[2:3]
	v_rcp_f32_e32 v32, v32
	v_rcp_f32_e32 v33, v33
	flat_store_dwordx4 v[48:49], v[40:43] offset:16
	flat_store_dwordx4 v[48:49], v[44:47]
	v_mul_f32_e32 v34, v34, v52
	v_lshlrev_b32_e32 v40, 16, v100
	v_and_b32_e32 v41, 0xffff0000, v100
	v_lshlrev_b32_e32 v42, 16, v96
	v_and_b32_e32 v43, 0xffff0000, v96
	v_pk_fma_f32 v[36:37], v[36:37], v[42:43], v[40:41]
	v_lshlrev_b32_e32 v40, 16, v101
	v_and_b32_e32 v41, 0xffff0000, v101
	v_lshlrev_b32_e32 v42, 16, v97
	v_and_b32_e32 v43, 0xffff0000, v97
	v_pk_fma_f32 v[38:39], v[38:39], v[42:43], v[40:41]
	v_lshlrev_b32_e32 v40, 16, v102
	v_and_b32_e32 v41, 0xffff0000, v102
	v_lshlrev_b32_e32 v42, 16, v98
	v_and_b32_e32 v43, 0xffff0000, v98
	v_pk_fma_f32 v[32:33], v[32:33], v[42:43], v[40:41]
	v_fmamk_f32 v43, v142, 0x3a000000, v205
	v_mul_f32_e32 v44, 0x4b800000, v43
	v_cmp_gt_f32_e32 vcc, s40, v43
	flat_store_dwordx4 v[48:49], v[36:39] offset:128
	v_mul_f32_e32 v35, v35, v52
	v_cndmask_b32_e32 v43, v43, v44, vcc
	v_rsq_f32_e32 v44, v43
	v_exp_f32_e32 v34, v34
	v_exp_f32_e32 v35, v35
	v_lshlrev_b32_e32 v40, 16, v103
	v_mul_f32_e32 v36, 0x45800000, v44
	v_cndmask_b32_e32 v36, v44, v36, vcc
	v_mul_f32_e32 v36, 0xbfb8aa3b, v36
	v_mul_f32_e32 v28, v28, v36
	v_mul_f32_e32 v29, v29, v36
	v_exp_f32_e32 v28, v28
	v_exp_f32_e32 v29, v29
	v_mul_f32_e32 v30, v30, v36
	v_mul_f32_e32 v31, v31, v36
	v_exp_f32_e32 v30, v30
	v_exp_f32_e32 v31, v31
	v_mul_f32_e32 v24, v24, v36
	v_mul_f32_e32 v25, v25, v36
	v_add_f32_e32 v34, 1.0, v34
	v_add_f32_e32 v35, 1.0, v35
	v_exp_f32_e32 v24, v24
	v_exp_f32_e32 v25, v25
	v_mul_f32_e32 v26, v26, v36
	v_mul_f32_e32 v27, v27, v36
	v_rcp_f32_e32 v34, v34
	v_rcp_f32_e32 v35, v35
	v_exp_f32_e32 v26, v26
	v_exp_f32_e32 v27, v27
	v_add_f32_e32 v28, 1.0, v28
	v_add_f32_e32 v29, 1.0, v29
	v_mul_f32_e32 v20, v20, v36
	v_mul_f32_e32 v21, v21, v36
	v_rcp_f32_e32 v28, v28
	v_rcp_f32_e32 v29, v29
	v_add_f32_e32 v30, 1.0, v30
	v_add_f32_e32 v31, 1.0, v31
	v_exp_f32_e32 v20, v20
	v_exp_f32_e32 v21, v21
	v_mul_f32_e32 v22, v22, v36
	v_mul_f32_e32 v23, v23, v36
	v_and_b32_e32 v41, 0xffff0000, v103
	v_lshlrev_b32_e32 v42, 16, v99
	v_and_b32_e32 v43, 0xffff0000, v99
	v_rcp_f32_e32 v30, v30
	v_rcp_f32_e32 v31, v31
	v_add_f32_e32 v24, 1.0, v24
	v_add_f32_e32 v25, 1.0, v25
	v_exp_f32_e32 v22, v22
	v_exp_f32_e32 v23, v23
	v_mul_f32_e32 v16, v16, v36
	v_mul_f32_e32 v17, v17, v36
	v_pk_fma_f32 v[34:35], v[34:35], v[42:43], v[40:41]
	v_rcp_f32_e32 v24, v24
	v_rcp_f32_e32 v25, v25
	v_add_f32_e32 v26, 1.0, v26
	v_add_f32_e32 v27, 1.0, v27
	v_exp_f32_e32 v16, v16
	v_exp_f32_e32 v17, v17
	flat_store_dwordx4 v[48:49], v[32:35] offset:144
	v_rcp_f32_e32 v26, v26
	v_rcp_f32_e32 v27, v27
	v_lshlrev_b32_e32 v32, 16, v92
	v_and_b32_e32 v33, 0xffff0000, v92
	v_lshlrev_b32_e32 v34, 16, v88
	v_and_b32_e32 v35, 0xffff0000, v88
	v_pk_fma_f32 v[28:29], v[28:29], v[34:35], v[32:33]
	v_lshlrev_b32_e32 v32, 16, v93
	v_and_b32_e32 v33, 0xffff0000, v93
	v_lshlrev_b32_e32 v34, 16, v89
	v_and_b32_e32 v35, 0xffff0000, v89
	v_add_f32_e32 v20, 1.0, v20
	v_add_f32_e32 v21, 1.0, v21
	v_pk_fma_f32 v[30:31], v[30:31], v[34:35], v[32:33]
	v_lshlrev_b32_e32 v32, 16, v94
	v_and_b32_e32 v33, 0xffff0000, v94
	v_lshlrev_b32_e32 v34, 16, v90
	v_and_b32_e32 v35, 0xffff0000, v90
	v_rcp_f32_e32 v20, v20
	v_rcp_f32_e32 v21, v21
	v_add_f32_e32 v22, 1.0, v22
	v_add_f32_e32 v23, 1.0, v23
	v_pk_fma_f32 v[24:25], v[24:25], v[34:35], v[32:33]
	v_lshlrev_b32_e32 v32, 16, v95
	v_and_b32_e32 v33, 0xffff0000, v95
	v_lshlrev_b32_e32 v34, 16, v91
	v_and_b32_e32 v35, 0xffff0000, v91
; __device__ __forceinline__ float bflo(unsigned u) { return __uint_as_float(u << 16); }
; #define PG8_BAR __builtin_amdgcn_s_barrier()
; template <class Epi, bool ALIGN_EPI>
; __device__ __forceinline__ void gemm_phase(LAS unsigned char* lds, const Gemm g, const StaticOrder& S, const Epi& E, const int wid) {
;     ...
;         if (!has_next) break;
; #pragma unroll
;         for (int a = 0; a < 2; ++a)
; #pragma unroll
;             for (int b = 0; b < 2; ++b)
; #pragma unroll
;                 for (int m = 0; m < 4; ++m)
; #pragma unroll
;                     for (int n = 0; n < 2; ++n) acc[a][b][m][n] = (f32x4){0.f, 0.f, 0.f, 0.f};
;         cur = nxt; cA = nA; cB = nB; ++ui;
;         if constexpr (ALIGN_EPI) { if (wr == 1) PG8_BAR; }
;     __device__ __forceinline__ void operator()(const Acc& acc, const Unit& u, int wr, int wc, int fr, int fq) const {
;     ...
;             for (int m = 0; m < 4; ++m) {
;                 const int row = u.pm * 256 + ai * 128 + wr * 64 + m * 16 + fr;
;                 const float rs = rsqrtf(rsv[m] * (1.0f / DM) + EPS) * -1.4426950408889634f;
; #pragma unroll
;                 for (int bj = 0; bj < 2; ++bj) {
;                     const size_t off = (size_t)row * DM + colbase + 32 * bj;
;                     f32x4 h0 = hv[m][bj][0], h1 = hv[m][bj][1];
;                     const u32x4 p4 = pw[m][bj];
;                     const f32x4 a0 = acc[ai][bj][m][0], a1 = acc[ai][bj][m][1];
;                     h0.x += bflo(p4.x) * __builtin_amdgcn_rcpf(1.0f + __builtin_amdgcn_exp2f(a0.x * rs));
;                     h0.y += bfhi(p4.x) * __builtin_amdgcn_rcpf(1.0f + __builtin_amdgcn_exp2f(a0.y * rs));
;                     h0.z += bflo(p4.y) * __builtin_amdgcn_rcpf(1.0f + __builtin_amdgcn_exp2f(a0.z * rs));
;                     h0.w += bfhi(p4.y) * __builtin_amdgcn_rcpf(1.0f + __builtin_amdgcn_exp2f(a0.w * rs));
;                     h1.x += bflo(p4.z) * __builtin_amdgcn_rcpf(1.0f + __builtin_amdgcn_exp2f(a1.x * rs));
;                     h1.y += bfhi(p4.z) * __builtin_amdgcn_rcpf(1.0f + __builtin_amdgcn_exp2f(a1.y * rs));
;                     h1.z += bflo(p4.w) * __builtin_amdgcn_rcpf(1.0f + __builtin_amdgcn_exp2f(a1.z * rs));
;                     h1.w += bfhi(p4.w) * __builtin_amdgcn_rcpf(1.0f + __builtin_amdgcn_exp2f(a1.w * rs));
;                     *(f32x4*)(out + off) = h0; *(f32x4*)(out + off + 4) = h1;
	v_rcp_f32_e32 v22, v22
	v_rcp_f32_e32 v23, v23
	v_add_f32_e32 v16, 1.0, v16
	v_add_f32_e32 v17, 1.0, v17
	v_pk_fma_f32 v[26:27], v[26:27], v[34:35], v[32:33]
	v_lshl_add_u64 v[32:33], v[118:119], 2, s[2:3]
	v_rcp_f32_e32 v16, v16
	v_rcp_f32_e32 v17, v17
	flat_store_dwordx4 v[32:33], v[24:27] offset:16
	flat_store_dwordx4 v[32:33], v[28:31]
	v_mul_f32_e32 v18, v18, v36
	v_lshlrev_b32_e32 v24, 16, v84
	v_and_b32_e32 v25, 0xffff0000, v84
	v_lshlrev_b32_e32 v26, 16, v80
	v_and_b32_e32 v27, 0xffff0000, v80
	v_pk_fma_f32 v[20:21], v[20:21], v[26:27], v[24:25]
	v_lshlrev_b32_e32 v24, 16, v85
	v_and_b32_e32 v25, 0xffff0000, v85
	v_lshlrev_b32_e32 v26, 16, v81
	v_and_b32_e32 v27, 0xffff0000, v81
	v_pk_fma_f32 v[22:23], v[22:23], v[26:27], v[24:25]
	v_lshlrev_b32_e32 v24, 16, v86
	v_and_b32_e32 v25, 0xffff0000, v86
	v_lshlrev_b32_e32 v26, 16, v82
	v_and_b32_e32 v27, 0xffff0000, v82
	v_pk_fma_f32 v[16:17], v[16:17], v[26:27], v[24:25]
	v_fmamk_f32 v27, v122, 0x3a000000, v205
	v_mul_f32_e32 v28, 0x4b800000, v27
	v_cmp_gt_f32_e32 vcc, s40, v27
	flat_store_dwordx4 v[32:33], v[20:23] offset:128
	v_mul_f32_e32 v19, v19, v36
	v_cndmask_b32_e32 v27, v27, v28, vcc
	v_rsq_f32_e32 v28, v27
	v_exp_f32_e32 v18, v18
	v_exp_f32_e32 v19, v19
	v_lshlrev_b32_e32 v24, 16, v87
	v_mul_f32_e32 v20, 0x45800000, v28
	v_cndmask_b32_e32 v20, v28, v20, vcc
	v_mul_f32_e32 v20, 0xbfb8aa3b, v20
	v_mul_f32_e32 v12, v12, v20
	v_mul_f32_e32 v13, v13, v20
	v_exp_f32_e32 v12, v12
	v_exp_f32_e32 v13, v13
	v_mul_f32_e32 v14, v14, v20
	v_mul_f32_e32 v15, v15, v20
	v_exp_f32_e32 v14, v14
	v_exp_f32_e32 v15, v15
	v_mul_f32_e32 v8, v8, v20
	v_mul_f32_e32 v9, v9, v20
	v_add_f32_e32 v18, 1.0, v18
	v_add_f32_e32 v19, 1.0, v19
	v_exp_f32_e32 v8, v8
	v_exp_f32_e32 v9, v9
	v_mul_f32_e32 v10, v10, v20
	v_mul_f32_e32 v11, v11, v20
	v_rcp_f32_e32 v18, v18
	v_rcp_f32_e32 v19, v19
	v_exp_f32_e32 v10, v10
	v_exp_f32_e32 v11, v11
	v_add_f32_e32 v12, 1.0, v12
	v_add_f32_e32 v13, 1.0, v13
	v_mul_f32_e32 v4, v4, v20
	v_mul_f32_e32 v5, v5, v20
	v_rcp_f32_e32 v12, v12
	v_rcp_f32_e32 v13, v13
	v_add_f32_e32 v14, 1.0, v14
	v_add_f32_e32 v15, 1.0, v15
	v_exp_f32_e32 v4, v4
	v_exp_f32_e32 v5, v5
	v_mul_f32_e32 v6, v6, v20
	v_mul_f32_e32 v7, v7, v20
	v_and_b32_e32 v25, 0xffff0000, v87
	v_lshlrev_b32_e32 v26, 16, v83
	v_and_b32_e32 v27, 0xffff0000, v83
	v_rcp_f32_e32 v14, v14
	v_rcp_f32_e32 v15, v15
	v_add_f32_e32 v8, 1.0, v8
	v_add_f32_e32 v9, 1.0, v9
	v_exp_f32_e32 v6, v6
	v_exp_f32_e32 v7, v7
	v_mul_f32_e32 v0, v0, v20
	v_mul_f32_e32 v1, v1, v20
	v_pk_fma_f32 v[18:19], v[18:19], v[26:27], v[24:25]
	v_rcp_f32_e32 v8, v8
	v_rcp_f32_e32 v9, v9
	v_add_f32_e32 v10, 1.0, v10
	v_add_f32_e32 v11, 1.0, v11
	v_exp_f32_e32 v0, v0
	v_exp_f32_e32 v1, v1
	v_mul_f32_e32 v2, v2, v20
	v_mul_f32_e32 v3, v3, v20
	flat_store_dwordx4 v[32:33], v[16:19] offset:144
	v_rcp_f32_e32 v10, v10
	v_rcp_f32_e32 v11, v11
	s_waitcnt vmcnt(0) lgkmcnt(0)
	v_lshlrev_b32_e32 v16, 16, v72
	v_and_b32_e32 v17, 0xffff0000, v72
	v_lshlrev_b32_e32 v18, 16, v76
	v_and_b32_e32 v19, 0xffff0000, v76
	v_exp_f32_e32 v2, v2
	v_exp_f32_e32 v3, v3
	v_pk_fma_f32 v[12:13], v[12:13], v[18:19], v[16:17]
	v_lshlrev_b32_e32 v16, 16, v73
	v_and_b32_e32 v17, 0xffff0000, v73
	v_lshlrev_b32_e32 v18, 16, v77
	v_and_b32_e32 v19, 0xffff0000, v77
	v_add_f32_e32 v4, 1.0, v4
	v_add_f32_e32 v5, 1.0, v5
	v_pk_fma_f32 v[14:15], v[14:15], v[18:19], v[16:17]
	v_lshlrev_b32_e32 v16, 16, v74
	v_and_b32_e32 v17, 0xffff0000, v74
	v_lshlrev_b32_e32 v18, 16, v78
	v_and_b32_e32 v19, 0xffff0000, v78
	v_rcp_f32_e32 v4, v4
	v_rcp_f32_e32 v5, v5
	v_add_f32_e32 v6, 1.0, v6
	v_add_f32_e32 v7, 1.0, v7
	v_pk_fma_f32 v[8:9], v[8:9], v[18:19], v[16:17]
	v_lshlrev_b32_e32 v16, 16, v75
	v_and_b32_e32 v17, 0xffff0000, v75
	v_lshlrev_b32_e32 v18, 16, v79
	v_and_b32_e32 v19, 0xffff0000, v79
	v_rcp_f32_e32 v6, v6
	v_rcp_f32_e32 v7, v7
	v_add_f32_e32 v0, 1.0, v0
	v_add_f32_e32 v1, 1.0, v1
	v_pk_fma_f32 v[10:11], v[10:11], v[18:19], v[16:17]
	v_lshl_add_u64 v[16:17], v[116:117], 2, s[2:3]
	v_rcp_f32_e32 v0, v0
	v_rcp_f32_e32 v1, v1
	v_add_f32_e32 v2, 1.0, v2
	v_add_f32_e32 v3, 1.0, v3
	flat_store_dwordx4 v[16:17], v[8:11] offset:16
	v_rcp_f32_e32 v2, v2
	v_rcp_f32_e32 v3, v3
	v_lshlrev_b32_e32 v8, 16, v64
	v_and_b32_e32 v9, 0xffff0000, v64
	v_lshlrev_b32_e32 v10, 16, v68
	v_and_b32_e32 v11, 0xffff0000, v68
	v_pk_fma_f32 v[4:5], v[4:5], v[10:11], v[8:9]
	v_lshlrev_b32_e32 v8, 16, v65
	v_and_b32_e32 v9, 0xffff0000, v65
	v_lshlrev_b32_e32 v10, 16, v69
	v_and_b32_e32 v11, 0xffff0000, v69
	v_pk_fma_f32 v[6:7], v[6:7], v[10:11], v[8:9]
	v_lshlrev_b32_e32 v8, 16, v66
	v_and_b32_e32 v9, 0xffff0000, v66
	v_lshlrev_b32_e32 v10, 16, v70
	v_and_b32_e32 v11, 0xffff0000, v70
	v_pk_fma_f32 v[0:1], v[0:1], v[10:11], v[8:9]
	v_lshlrev_b32_e32 v8, 16, v67
	v_and_b32_e32 v9, 0xffff0000, v67
	v_lshlrev_b32_e32 v10, 16, v71
	v_and_b32_e32 v11, 0xffff0000, v71
	s_andn2_b64 vcc, exec, s[4:5]
	s_mov_b64 s[4:5], -1
	flat_store_dwordx4 v[16:17], v[12:15]
	v_pk_fma_f32 v[2:3], v[2:3], v[10:11], v[8:9]
	flat_store_dwordx4 v[16:17], v[4:7] offset:128
	flat_store_dwordx4 v[16:17], v[0:3] offset:144
	s_cbranch_vccnz .LBB0_803
	s_and_b64 vcc, exec, s[0:1]
	s_cbranch_vccnz .LBB0_802
	s_barrier
	s_branch .LBB0_802
